# drain prefetch loads before each GEMM epilogue and skip the first two vmcnt waits of the next tile so its first load segments overlap the store drain
# speedup vs baseline: 1.0333x; 1.0041x over previous
.LBB0_702:
	s_add_i32 s47, s4, 2
	s_add_u32 s91, s2, 0x80
	s_addc_u32 s5, s3, 0
	s_add_i32 s93, 0, 0x10000
	s_cmp_eq_u32 s31, s4
	s_cselect_b32 s5, s87, s5
	s_cselect_b32 s4, s86, s91
	s_cselect_b32 s95, s89, s46
	s_cselect_b32 s94, s88, s7
	s_add_i32 s91, 0, 0x14000
	v_add_u32_e32 v140, s93, v195
	v_add_u32_e32 v156, s91, v195
	ds_read_b128 v[128:131], v140
	ds_read_b128 v[132:135], v140 offset:1024
	ds_read_b128 v[136:139], v140 offset:2048
	ds_read_b128 v[140:143], v140 offset:3072
	ds_read_b128 v[144:147], v156
	ds_read_b128 v[148:151], v156 offset:1024
	ds_read_b128 v[152:155], v156 offset:2048
	ds_read_b128 v[156:159], v156 offset:3072
	v_lshl_add_u64 v[208:209], s[2:3], 0, v[204:205]
	s_add_i32 m0, s20, 0xc000
	ds_read_b128 v[160:163], v246
	ds_read_b128 v[164:167], v246 offset:1024
	ds_read_b128 v[168:171], v246 offset:2048
	ds_read_b128 v[172:175], v246 offset:3072
	ds_read_b128 v[176:179], v246 offset:4096
	ds_read_b128 v[180:183], v246 offset:5120
	ds_read_b128 v[184:187], v246 offset:6144
	ds_read_b128 v[188:191], v246 offset:7168
	global_load_lds_dwordx4 v[208:209], off
	v_lshl_add_u64 v[208:209], s[2:3], 0, v[206:207]
	s_add_i32 m0, s20, 0xe000
	s_nop 0
	global_load_lds_dwordx4 v[208:209], off
	s_cmp_eq_u32 s34, 1
	s_cselect_b32 s100, 1, 0
	s_sub_i32 s101, s47, 2
	s_or_b32 s100, s100, s101
	s_cbranch_scc0 .Lkl_skipw1
	s_waitcnt vmcnt(8)
.Lkl_skipw1:
	s_waitcnt lgkmcnt(0)
	s_barrier
	s_setprio 1
	s_waitcnt lgkmcnt(0)
	v_mfma_f32_16x16x32_bf16 v[124:127], v[128:131], v[160:163], v[124:127]
	v_mfma_f32_16x16x32_bf16 v[60:63], v[136:139], v[160:163], v[60:63]
	v_mfma_f32_16x16x32_bf16 v[116:119], v[128:131], v[168:171], v[116:119]
	v_mfma_f32_16x16x32_bf16 v[52:55], v[136:139], v[168:171], v[52:55]
	v_mfma_f32_16x16x32_bf16 v[108:111], v[128:131], v[176:179], v[108:111]
	v_mfma_f32_16x16x32_bf16 v[44:47], v[136:139], v[176:179], v[44:47]
	v_mfma_f32_16x16x32_bf16 v[100:103], v[128:131], v[184:187], v[100:103]
	v_mfma_f32_16x16x32_bf16 v[36:39], v[136:139], v[184:187], v[36:39]
	v_mfma_f32_16x16x32_bf16 v[124:127], v[132:135], v[164:167], v[124:127]
	v_mfma_f32_16x16x32_bf16 v[60:63], v[140:143], v[164:167], v[60:63]
	v_mfma_f32_16x16x32_bf16 v[116:119], v[132:135], v[172:175], v[116:119]
	v_mfma_f32_16x16x32_bf16 v[52:55], v[140:143], v[172:175], v[52:55]
	v_mfma_f32_16x16x32_bf16 v[108:111], v[132:135], v[180:183], v[108:111]
	v_mfma_f32_16x16x32_bf16 v[44:47], v[140:143], v[180:183], v[44:47]
	v_mfma_f32_16x16x32_bf16 v[100:103], v[132:135], v[188:191], v[100:103]
	v_mfma_f32_16x16x32_bf16 v[36:39], v[140:143], v[188:191], v[36:39]
	s_setprio 0
	s_setprio 1
	v_mfma_f32_16x16x32_bf16 v[120:123], v[144:147], v[160:163], v[120:123]
	v_mfma_f32_16x16x32_bf16 v[56:59], v[152:155], v[160:163], v[56:59]
	v_mfma_f32_16x16x32_bf16 v[112:115], v[144:147], v[168:171], v[112:115]
	v_mfma_f32_16x16x32_bf16 v[48:51], v[152:155], v[168:171], v[48:51]
	v_mfma_f32_16x16x32_bf16 v[104:107], v[144:147], v[176:179], v[104:107]
	v_mfma_f32_16x16x32_bf16 v[40:43], v[152:155], v[176:179], v[40:43]
	v_mfma_f32_16x16x32_bf16 v[96:99], v[144:147], v[184:187], v[96:99]
	v_mfma_f32_16x16x32_bf16 v[32:35], v[152:155], v[184:187], v[32:35]
	v_mfma_f32_16x16x32_bf16 v[120:123], v[148:151], v[164:167], v[120:123]
	v_mfma_f32_16x16x32_bf16 v[56:59], v[156:159], v[164:167], v[56:59]
	v_mfma_f32_16x16x32_bf16 v[112:115], v[148:151], v[172:175], v[112:115]
	v_mfma_f32_16x16x32_bf16 v[48:51], v[156:159], v[172:175], v[48:51]
	v_mfma_f32_16x16x32_bf16 v[104:107], v[148:151], v[180:183], v[104:107]
	v_mfma_f32_16x16x32_bf16 v[40:43], v[156:159], v[180:183], v[40:43]
	v_mfma_f32_16x16x32_bf16 v[96:99], v[148:151], v[188:191], v[96:99]
	v_mfma_f32_16x16x32_bf16 v[32:35], v[156:159], v[188:191], v[32:35]
	s_setprio 0
	s_barrier
	s_add_i32 s93, s93, s83
	v_lshl_add_u64 v[208:209], s[94:95], 0, v[202:203]
	s_mov_b32 m0, s93
	ds_read_b128 v[160:163], v246 offset:16384
	ds_read_b128 v[164:167], v246 offset:17408
	ds_read_b128 v[168:171], v246 offset:18432
	ds_read_b128 v[172:175], v246 offset:19456
	ds_read_b128 v[176:179], v246 offset:20480
	ds_read_b128 v[180:183], v246 offset:21504
	ds_read_b128 v[184:187], v246 offset:22528
	ds_read_b128 v[188:191], v246 offset:23552
	global_load_lds_dwordx4 v[208:209], off
	s_add_i32 m0, s93, 0x2000
	v_lshl_add_u64 v[210:211], s[94:95], 0, v[198:199]
	s_add_u32 s94, s94, s50
	s_addc_u32 s95, s95, s51
	s_add_i32 s91, s91, s83
	global_load_lds_dwordx4 v[210:211], off
	v_lshl_add_u64 v[212:213], s[94:95], 0, v[202:203]
	s_mov_b32 m0, s91
	v_lshl_add_u64 v[214:215], s[94:95], 0, v[198:199]
	global_load_lds_dwordx4 v[212:213], off
	s_add_i32 m0, s91, 0x2000
	v_lshl_add_u64 v[216:217], s[4:5], 0, v[200:201]
	global_load_lds_dwordx4 v[214:215], off
	s_mov_b32 m0, s20
	v_lshl_add_u64 v[218:219], s[4:5], 0, v[196:197]
	global_load_lds_dwordx4 v[216:217], off
	s_mov_b32 m0, s21
	s_nop 0
	global_load_lds_dwordx4 v[218:219], off
	s_cmp_eq_u32 s34, 1
	s_cselect_b32 s100, 1, 0
	s_sub_i32 s101, s47, 2
	s_or_b32 s100, s100, s101
	s_cbranch_scc0 .Lkl_skipw2
	s_waitcnt vmcnt(8)
.Lkl_skipw2:
	s_waitcnt lgkmcnt(0)
	s_barrier
	s_setprio 1
	s_waitcnt lgkmcnt(0)
	v_mfma_f32_16x16x32_bf16 v[92:95], v[128:131], v[160:163], v[92:95]
	v_mfma_f32_16x16x32_bf16 v[28:31], v[136:139], v[160:163], v[28:31]
	v_mfma_f32_16x16x32_bf16 v[84:87], v[128:131], v[168:171], v[84:87]
	v_mfma_f32_16x16x32_bf16 v[20:23], v[136:139], v[168:171], v[20:23]
	v_mfma_f32_16x16x32_bf16 v[76:79], v[128:131], v[176:179], v[76:79]
	v_mfma_f32_16x16x32_bf16 v[12:15], v[136:139], v[176:179], v[12:15]
	v_mfma_f32_16x16x32_bf16 v[68:71], v[128:131], v[184:187], v[68:71]
	v_mfma_f32_16x16x32_bf16 v[4:7], v[136:139], v[184:187], v[4:7]
	v_mfma_f32_16x16x32_bf16 v[92:95], v[132:135], v[164:167], v[92:95]
	v_mfma_f32_16x16x32_bf16 v[28:31], v[140:143], v[164:167], v[28:31]
	v_mfma_f32_16x16x32_bf16 v[84:87], v[132:135], v[172:175], v[84:87]
	v_mfma_f32_16x16x32_bf16 v[20:23], v[140:143], v[172:175], v[20:23]
	v_mfma_f32_16x16x32_bf16 v[76:79], v[132:135], v[180:183], v[76:79]
	v_mfma_f32_16x16x32_bf16 v[12:15], v[140:143], v[180:183], v[12:15]
	v_mfma_f32_16x16x32_bf16 v[68:71], v[132:135], v[188:191], v[68:71]
	v_mfma_f32_16x16x32_bf16 v[4:7], v[140:143], v[188:191], v[4:7]
	s_setprio 0
	s_setprio 1
	v_mfma_f32_16x16x32_bf16 v[88:91], v[144:147], v[160:163], v[88:91]
	v_mfma_f32_16x16x32_bf16 v[24:27], v[152:155], v[160:163], v[24:27]
	v_mfma_f32_16x16x32_bf16 v[80:83], v[144:147], v[168:171], v[80:83]
	v_mfma_f32_16x16x32_bf16 v[16:19], v[152:155], v[168:171], v[16:19]
	v_mfma_f32_16x16x32_bf16 v[72:75], v[144:147], v[176:179], v[72:75]
	v_mfma_f32_16x16x32_bf16 v[8:11], v[152:155], v[176:179], v[8:11]
	v_mfma_f32_16x16x32_bf16 v[64:67], v[144:147], v[184:187], v[64:67]
	v_mfma_f32_16x16x32_bf16 v[0:3], v[152:155], v[184:187], v[0:3]
	v_mfma_f32_16x16x32_bf16 v[88:91], v[148:151], v[164:167], v[88:91]
	v_mfma_f32_16x16x32_bf16 v[24:27], v[156:159], v[164:167], v[24:27]
	v_mfma_f32_16x16x32_bf16 v[80:83], v[148:151], v[172:175], v[80:83]
	v_mfma_f32_16x16x32_bf16 v[16:19], v[156:159], v[172:175], v[16:19]
	v_mfma_f32_16x16x32_bf16 v[72:75], v[148:151], v[180:183], v[72:75]
	v_mfma_f32_16x16x32_bf16 v[8:11], v[156:159], v[180:183], v[8:11]
	v_mfma_f32_16x16x32_bf16 v[64:67], v[148:151], v[188:191], v[64:67]
	v_mfma_f32_16x16x32_bf16 v[0:3], v[156:159], v[188:191], v[0:3]
	s_setprio 0
	s_barrier
	v_add_u32_e32 v140, s17, v195
	v_add_u32_e32 v156, s66, v195
	ds_read_b128 v[128:131], v140
	ds_read_b128 v[132:135], v140 offset:1024
	ds_read_b128 v[136:139], v140 offset:2048
	ds_read_b128 v[140:143], v140 offset:3072
	ds_read_b128 v[144:147], v156
	ds_read_b128 v[148:151], v156 offset:1024
	ds_read_b128 v[152:155], v156 offset:2048
	ds_read_b128 v[156:159], v156 offset:3072
	s_add_u32 s4, s4, s50
	s_addc_u32 s5, s5, s51
	s_mov_b32 m0, s26
	v_lshl_add_u64 v[220:221], s[4:5], 0, v[200:201]
	ds_read_b128 v[160:163], v246 offset:32768
	ds_read_b128 v[164:167], v246 offset:33792
	ds_read_b128 v[168:171], v246 offset:34816
	ds_read_b128 v[172:175], v246 offset:35840
	ds_read_b128 v[176:179], v246 offset:36864
	ds_read_b128 v[180:183], v246 offset:37888
	ds_read_b128 v[184:187], v246 offset:38912
	ds_read_b128 v[188:191], v246 offset:39936
	global_load_lds_dwordx4 v[220:221], off
	v_lshl_add_u64 v[220:221], s[4:5], 0, v[196:197]
	s_mov_b32 m0, s27
	s_nop 0
	global_load_lds_dwordx4 v[220:221], off
	s_waitcnt vmcnt(8)
	s_waitcnt lgkmcnt(0)
	s_barrier
	s_setprio 1
	s_waitcnt lgkmcnt(0)
	v_mfma_f32_16x16x32_bf16 v[124:127], v[128:131], v[160:163], v[124:127]
	v_mfma_f32_16x16x32_bf16 v[60:63], v[136:139], v[160:163], v[60:63]
	v_mfma_f32_16x16x32_bf16 v[116:119], v[128:131], v[168:171], v[116:119]
	v_mfma_f32_16x16x32_bf16 v[52:55], v[136:139], v[168:171], v[52:55]
	v_mfma_f32_16x16x32_bf16 v[108:111], v[128:131], v[176:179], v[108:111]
	v_mfma_f32_16x16x32_bf16 v[44:47], v[136:139], v[176:179], v[44:47]
	v_mfma_f32_16x16x32_bf16 v[100:103], v[128:131], v[184:187], v[100:103]
	v_mfma_f32_16x16x32_bf16 v[36:39], v[136:139], v[184:187], v[36:39]
	v_mfma_f32_16x16x32_bf16 v[124:127], v[132:135], v[164:167], v[124:127]
	v_mfma_f32_16x16x32_bf16 v[60:63], v[140:143], v[164:167], v[60:63]
	v_mfma_f32_16x16x32_bf16 v[116:119], v[132:135], v[172:175], v[116:119]
	v_mfma_f32_16x16x32_bf16 v[52:55], v[140:143], v[172:175], v[52:55]
	v_mfma_f32_16x16x32_bf16 v[108:111], v[132:135], v[180:183], v[108:111]
	v_mfma_f32_16x16x32_bf16 v[44:47], v[140:143], v[180:183], v[44:47]
	v_mfma_f32_16x16x32_bf16 v[100:103], v[132:135], v[188:191], v[100:103]
	v_mfma_f32_16x16x32_bf16 v[36:39], v[140:143], v[188:191], v[36:39]
	s_setprio 0
	s_setprio 1
	v_mfma_f32_16x16x32_bf16 v[120:123], v[144:147], v[160:163], v[120:123]
	v_mfma_f32_16x16x32_bf16 v[56:59], v[152:155], v[160:163], v[56:59]
	v_mfma_f32_16x16x32_bf16 v[112:115], v[144:147], v[168:171], v[112:115]
	v_mfma_f32_16x16x32_bf16 v[48:51], v[152:155], v[168:171], v[48:51]
	v_mfma_f32_16x16x32_bf16 v[104:107], v[144:147], v[176:179], v[104:107]
	v_mfma_f32_16x16x32_bf16 v[40:43], v[152:155], v[176:179], v[40:43]
	v_mfma_f32_16x16x32_bf16 v[96:99], v[144:147], v[184:187], v[96:99]
	v_mfma_f32_16x16x32_bf16 v[32:35], v[152:155], v[184:187], v[32:35]
	v_mfma_f32_16x16x32_bf16 v[120:123], v[148:151], v[164:167], v[120:123]
	v_mfma_f32_16x16x32_bf16 v[56:59], v[156:159], v[164:167], v[56:59]
	v_mfma_f32_16x16x32_bf16 v[112:115], v[148:151], v[172:175], v[112:115]
	v_mfma_f32_16x16x32_bf16 v[48:51], v[156:159], v[172:175], v[48:51]
	v_mfma_f32_16x16x32_bf16 v[104:107], v[148:151], v[180:183], v[104:107]
	v_mfma_f32_16x16x32_bf16 v[40:43], v[156:159], v[180:183], v[40:43]
	v_mfma_f32_16x16x32_bf16 v[96:99], v[148:151], v[188:191], v[96:99]
	v_mfma_f32_16x16x32_bf16 v[32:35], v[156:159], v[188:191], v[32:35]
	s_setprio 0
	s_barrier
	s_add_i32 s4, s17, s83
	v_lshl_add_u64 v[208:209], v[208:209], 0, s[38:39]
	s_mov_b32 m0, s4
	ds_read_b128 v[160:163], v246 offset:49152
	ds_read_b128 v[164:167], v246 offset:50176
	ds_read_b128 v[168:171], v246 offset:51200
	ds_read_b128 v[172:175], v246 offset:52224
	ds_read_b128 v[176:179], v246 offset:53248
	ds_read_b128 v[180:183], v246 offset:54272
	ds_read_b128 v[184:187], v246 offset:55296
	ds_read_b128 v[188:191], v246 offset:56320
	global_load_lds_dwordx4 v[208:209], off
	v_lshl_add_u64 v[208:209], v[210:211], 0, s[38:39]
	s_add_i32 m0, s4, 0x2000
	s_add_i32 s4, s66, s83
	global_load_lds_dwordx4 v[208:209], off
	v_lshl_add_u64 v[208:209], v[212:213], 0, s[38:39]
	s_mov_b32 m0, s4
	s_nop 0
	global_load_lds_dwordx4 v[208:209], off
	v_lshl_add_u64 v[208:209], v[214:215], 0, s[38:39]
	s_add_i32 m0, s4, 0x2000
	s_nop 0
	global_load_lds_dwordx4 v[208:209], off
	v_lshl_add_u64 v[208:209], v[216:217], 0, s[38:39]
	s_mov_b32 m0, s54
	s_nop 0
	global_load_lds_dwordx4 v[208:209], off
	v_lshl_add_u64 v[208:209], v[218:219], 0, s[38:39]
	s_mov_b32 m0, s55
	s_nop 0
	global_load_lds_dwordx4 v[208:209], off
	s_waitcnt vmcnt(8)
	s_waitcnt lgkmcnt(0)
	s_barrier
	s_setprio 1
	s_waitcnt lgkmcnt(0)
	v_mfma_f32_16x16x32_bf16 v[92:95], v[128:131], v[160:163], v[92:95]
	v_mfma_f32_16x16x32_bf16 v[28:31], v[136:139], v[160:163], v[28:31]
	v_mfma_f32_16x16x32_bf16 v[84:87], v[128:131], v[168:171], v[84:87]
	v_mfma_f32_16x16x32_bf16 v[20:23], v[136:139], v[168:171], v[20:23]
	v_mfma_f32_16x16x32_bf16 v[76:79], v[128:131], v[176:179], v[76:79]
	v_mfma_f32_16x16x32_bf16 v[12:15], v[136:139], v[176:179], v[12:15]
	v_mfma_f32_16x16x32_bf16 v[68:71], v[128:131], v[184:187], v[68:71]
	v_mfma_f32_16x16x32_bf16 v[4:7], v[136:139], v[184:187], v[4:7]
	v_mfma_f32_16x16x32_bf16 v[92:95], v[132:135], v[164:167], v[92:95]
	v_mfma_f32_16x16x32_bf16 v[28:31], v[140:143], v[164:167], v[28:31]
	v_mfma_f32_16x16x32_bf16 v[84:87], v[132:135], v[172:175], v[84:87]
	v_mfma_f32_16x16x32_bf16 v[20:23], v[140:143], v[172:175], v[20:23]
	v_mfma_f32_16x16x32_bf16 v[76:79], v[132:135], v[180:183], v[76:79]
	v_mfma_f32_16x16x32_bf16 v[12:15], v[140:143], v[180:183], v[12:15]
	v_mfma_f32_16x16x32_bf16 v[68:71], v[132:135], v[188:191], v[68:71]
	v_mfma_f32_16x16x32_bf16 v[4:7], v[140:143], v[188:191], v[4:7]
	s_setprio 0
	s_setprio 1
	v_mfma_f32_16x16x32_bf16 v[88:91], v[144:147], v[160:163], v[88:91]
	v_mfma_f32_16x16x32_bf16 v[24:27], v[152:155], v[160:163], v[24:27]
	v_mfma_f32_16x16x32_bf16 v[80:83], v[144:147], v[168:171], v[80:83]
	v_mfma_f32_16x16x32_bf16 v[16:19], v[152:155], v[168:171], v[16:19]
	v_mfma_f32_16x16x32_bf16 v[72:75], v[144:147], v[176:179], v[72:75]
	v_mfma_f32_16x16x32_bf16 v[8:11], v[152:155], v[176:179], v[8:11]
	v_mfma_f32_16x16x32_bf16 v[64:67], v[144:147], v[184:187], v[64:67]
	v_mfma_f32_16x16x32_bf16 v[0:3], v[152:155], v[184:187], v[0:3]
	v_mfma_f32_16x16x32_bf16 v[88:91], v[148:151], v[164:167], v[88:91]
	v_mfma_f32_16x16x32_bf16 v[24:27], v[156:159], v[164:167], v[24:27]
	v_mfma_f32_16x16x32_bf16 v[80:83], v[148:151], v[172:175], v[80:83]
	v_mfma_f32_16x16x32_bf16 v[16:19], v[156:159], v[172:175], v[16:19]
	v_mfma_f32_16x16x32_bf16 v[72:75], v[148:151], v[180:183], v[72:75]
	v_mfma_f32_16x16x32_bf16 v[8:11], v[156:159], v[180:183], v[8:11]
	v_mfma_f32_16x16x32_bf16 v[64:67], v[148:151], v[188:191], v[64:67]
	v_mfma_f32_16x16x32_bf16 v[0:3], v[156:159], v[188:191], v[0:3]
	s_setprio 0
	s_barrier
	s_add_u32 s2, s2, 0x100
	s_addc_u32 s3, s3, 0
	s_add_u32 s7, s7, 0x100
	s_addc_u32 s46, s46, 0
	s_cmp_ge_u32 s47, s56
	s_mov_b32 s4, s47
	s_cbranch_scc0 .LBB0_702
	s_and_b64 vcc, exec, s[0:1]
	s_cbranch_vccz .LBB0_705
	s_barrier
.LBB0_705:
	s_waitcnt vmcnt(0)
	v_mov_b32_e32 v247, v245
	s_mov_b64 s[2:3], -1
	v_and_b32_e32 v192, 15, v247
	s_and_b64 vcc, exec, s[48:49]
	v_readlane_b32 s93, v254, 11
	s_cbranch_vccz .LBB0_710
	v_ashrrev_i32_e32 v248, 4, v247
	s_mov_b64 s[46:47], -1
	s_mov_b64 s[2:3], 0
	s_cmp_lt_i32 s82, 2
	s_mov_b64 s[4:5], 0
	s_cbranch_scc1 .LBB0_719
	s_cmp_eq_u32 s82, 2
	s_mov_b64 s[4:5], -1
	s_cbranch_scc0 .LBB0_844
	s_cmp_lg_u32 s11, 0
	s_cselect_b64 s[46:47], -1, 0
	s_cmp_eq_u32 s11, 0
	s_cbranch_scc1 .LBB0_758
	s_mul_hi_i32 s5, s92, 0x1800
	s_mul_i32 s4, s92, 0x1800
	s_branch .LBB0_759
